# attention tile loop: K/V pointer advances moved into the shadow of the first LDS wait (right after the global loads)
# speedup vs baseline: 1.0090x; 1.0090x over previous
.LBB0_175:
	s_barrier
	ds_read_b128 v[162:165], v104
	ds_read_b128 v[166:169], v104 offset:64
	ds_read_b128 v[170:173], v104 offset:128
	ds_read_b128 v[174:177], v104 offset:3584
	ds_read_b128 v[178:181], v104 offset:3648
	ds_read_b128 v[182:185], v104 offset:3712
	ds_read_b128 v[186:189], v104 offset:7168
	ds_read_b128 v[214:217], v104 offset:7232
	ds_read_b128 v[218:221], v104 offset:7296
	ds_read_b128 v[222:225], v104 offset:10752
	ds_read_b128 v[226:229], v104 offset:10816
	ds_read_b128 v[230:233], v104 offset:10880
	global_load_dwordx4 v[72:75], v[136:137], off
	global_load_dwordx4 v[68:71], v[134:135], off
	global_load_dwordx4 v[64:67], v[132:133], off
	v_lshl_add_u64 v[132:133], v[132:133], 0, s[50:51]
	v_lshl_add_u64 v[134:135], v[134:135], 0, s[4:5]
	v_lshl_add_u64 v[136:137], v[136:137], 0, s[4:5]
	s_and_b32 s21, s7, 15
	s_cbranch_scc0 .Lattn_refresh
	s_waitcnt lgkmcnt(9)
	v_mfma_f32_16x16x32_bf16 v[92:95], v[162:165], v[0:3], v[148:151]
	v_mfma_f32_16x16x32_bf16 v[76:79], v[162:165], v[8:11], v[152:155]
	ds_read_b64 v[234:235], v147 offset:14336
	ds_read_b64 v[236:237], v147 offset:14368
	v_mfma_f32_16x16x32_bf16 v[92:95], v[166:169], v[4:7], v[92:95]
	v_mfma_f32_16x16x32_bf16 v[76:79], v[166:169], v[12:15], v[76:79]
	ds_read_b64 v[238:239], v147 offset:14400
	ds_read_b64 v[240:241], v147 offset:14432
	v_mfma_f32_16x16x32_bf16 v[92:95], v[170:173], v[16:19], v[92:95]
	v_mfma_f32_16x16x32_bf16 v[76:79], v[170:173], v[20:23], v[76:79]
	ds_read_b64 v[242:243], v147 offset:16640
	ds_read_b64 v[244:245], v147 offset:16672
	s_waitcnt lgkmcnt(12)
	v_mfma_f32_16x16x32_bf16 v[96:99], v[174:177], v[0:3], v[148:151]
	v_mfma_f32_16x16x32_bf16 v[80:83], v[174:177], v[8:11], v[152:155]
	ds_read_b64 v[246:247], v147 offset:16704
	v_mfma_f32_16x16x32_bf16 v[96:99], v[178:181], v[4:7], v[96:99]
	v_mfma_f32_16x16x32_bf16 v[80:83], v[178:181], v[12:15], v[80:83]
	ds_read_b64 v[248:249], v147 offset:16736
	v_mfma_f32_16x16x32_bf16 v[96:99], v[182:185], v[16:19], v[96:99]
	v_mfma_f32_16x16x32_bf16 v[80:83], v[182:185], v[20:23], v[80:83]
	ds_read_b64 v[162:163], v147 offset:18944
	s_waitcnt lgkmcnt(12)
	v_mfma_f32_16x16x32_bf16 v[100:103], v[186:189], v[0:3], v[148:151]
	v_mfma_f32_16x16x32_bf16 v[84:87], v[186:189], v[8:11], v[152:155]
	ds_read_b64 v[164:165], v147 offset:18976
	v_mfma_f32_16x16x32_bf16 v[100:103], v[214:217], v[4:7], v[100:103]
	v_mfma_f32_16x16x32_bf16 v[84:87], v[214:217], v[12:15], v[84:87]
	ds_read_b64 v[166:167], v147 offset:19008
	v_mfma_f32_16x16x32_bf16 v[100:103], v[218:221], v[16:19], v[100:103]
	v_mfma_f32_16x16x32_bf16 v[84:87], v[218:221], v[20:23], v[84:87]
	ds_read_b64 v[168:169], v147 offset:19040
	s_waitcnt lgkmcnt(12)
	v_mfma_f32_16x16x32_bf16 v[104:107], v[222:225], v[0:3], v[148:151]
	v_mfma_f32_16x16x32_bf16 v[88:91], v[222:225], v[8:11], v[152:155]
	ds_read_b64 v[170:171], v147 offset:21248
	v_mfma_f32_16x16x32_bf16 v[104:107], v[226:229], v[4:7], v[104:107]
	v_mfma_f32_16x16x32_bf16 v[88:91], v[226:229], v[12:15], v[88:91]
	ds_read_b64 v[172:173], v147 offset:21280
	v_mfma_f32_16x16x32_bf16 v[104:107], v[230:233], v[16:19], v[104:107]
	v_mfma_f32_16x16x32_bf16 v[88:91], v[230:233], v[20:23], v[88:91]
	s_waitcnt lgkmcnt(13)
	ds_read_b64 v[174:175], v147 offset:21312
	ds_read_b64 v[176:177], v147 offset:21344

.Lattn_skipw:
	s_waitcnt lgkmcnt(14)
	v_mfma_f32_16x16x32_bf16 v[60:63], v[234:237], v[92:95], v[60:63]
	v_mfma_f32_16x16x32_bf16 v[56:59], v[234:237], v[76:79], v[56:59]
	v_mfma_f32_16x16x32_bf16 v[60:63], v[238:241], v[96:99], v[60:63]
	v_mfma_f32_16x16x32_bf16 v[56:59], v[238:241], v[80:83], v[56:59]
	s_waitcnt lgkmcnt(10)
	v_mfma_f32_16x16x32_bf16 v[52:55], v[242:245], v[92:95], v[52:55]
	v_mfma_f32_16x16x32_bf16 v[48:51], v[242:245], v[76:79], v[48:51]
	v_mfma_f32_16x16x32_bf16 v[52:55], v[246:249], v[96:99], v[52:55]
	v_mfma_f32_16x16x32_bf16 v[48:51], v[246:249], v[80:83], v[48:51]
	s_waitcnt lgkmcnt(6)
	v_mfma_f32_16x16x32_bf16 v[44:47], v[162:165], v[92:95], v[44:47]
	v_mfma_f32_16x16x32_bf16 v[40:43], v[162:165], v[76:79], v[40:43]
	v_mfma_f32_16x16x32_bf16 v[44:47], v[166:169], v[96:99], v[44:47]
	v_mfma_f32_16x16x32_bf16 v[40:43], v[166:169], v[80:83], v[40:43]
	s_waitcnt lgkmcnt(2)
	v_mfma_f32_16x16x32_bf16 v[36:39], v[170:173], v[92:95], v[36:39]
	v_mfma_f32_16x16x32_bf16 v[32:35], v[170:173], v[76:79], v[32:35]
	v_mfma_f32_16x16x32_bf16 v[36:39], v[174:177], v[96:99], v[36:39]
	v_mfma_f32_16x16x32_bf16 v[32:35], v[174:177], v[80:83], v[32:35]
	v_mfma_f32_16x16x32_bf16 v[28:31], v[250:253], v[92:95], v[28:31]
	v_mfma_f32_16x16x32_bf16 v[24:27], v[250:253], v[76:79], v[24:27]
	v_mfma_f32_16x16x32_bf16 v[28:31], v[250:253], v[96:99], v[28:31]
	v_mfma_f32_16x16x32_bf16 v[24:27], v[250:253], v[80:83], v[24:27]
	v_add3_u32 v104, s10, v110, v142
	v_add3_u32 v147, s10, v138, v143
	s_cmp_eq_u32 s6, s7
	s_waitcnt lgkmcnt(0)
	s_cbranch_scc0 .LBB0_175
	s_barrier
	s_branch .LBB0_161
